# phase-1 tail: transposes wave mapping rotated so the double-item waves and the item-less waves land on the lighter / heavier workgroups respectively, on top of previous best
# speedup vs baseline: 1.0017x; 1.0017x over previous
; #define LAS __attribute__((address_space(3)))
; #define P (*args_here())
; DI void p0_transposes(const Ptrs& P, LAS unsigned char* lds, int lo, int hi, int w, int NW, int wave, int lane) {
;     unsigned char* ws = P.ws;
;     LAS float* scr = (LAS float*)(lds + RING_OFF + wave * 16384);
;     for (int it = lo + w; it < hi; it += NW) {
;         int r = it;
;         if (r < 4 * P0_I_GU) {
;             const int which = r / P0_I_GU; r -= which * P0_I_GU; const int nblk = FF / 32, kb = r / nblk, nb = r % nblk;
;             const float* W = which == 0 ? P.in[9] : which == 1 ? P.in[10] : which == 2 ? P.in[32] : P.in[33];
;             bf16* WT = (bf16*)(ws + (which < 2 ? WS_WGUA : WS_WGUB));
;             p0_transpose_item(W, DM, FF, WT, kb, nb, gu_row(32 * nb, which & 1), scr, lane); continue; }
;         r -= 4 * P0_I_GU;
;         if (r < 2 * P0_I_D) { const int which = r / P0_I_D; r -= which * P0_I_D; const int nblk = DM / 32, kb = r / nblk, nb = r % nblk;
;             p0_transpose_item(which ? P.in[34] : P.in[11], FF, DM, (bf16*)(ws + (which ? WS_WDB : WS_WDA)), kb, nb, 32 * nb, scr, lane); continue; }
; DI void p0_tail1(const Ptrs& P, LAS unsigned char* lds, int bx, int tid, int wave, int lane) {
;     if (bx < 88) return;
;     const int w = (bx - 88) * NWAVES + wave, NW = 168 * NWAVES;
;     p0_transposes(P, lds, P0_DA, P0_DB, w, NW, wave, lane); p0_transposes(P, lds, P0_IN, P0_END, w, NW, wave, lane);
.LBB0_92:
	s_mov_b64 s[2:3], s[96:97]
	s_cmpk_lt_i32 s33, 0x58
	s_cbranch_scc1 .LBB0_142
	s_add_i32 s0, s33, 0xffffffa8
	s_load_dwordx2 s[4:5], s[2:3], 0x130
	s_lshl_b32 s1, s0, 3
	v_readlane_b32 s6, v254, 9
	s_add_i32 s1, s6, s1
	s_add_i32 s6, s1, 0x1600
	s_cmpk_gt_i32 s6, 0x1b7f
	v_readlane_b32 s7, v254, 10
	s_cbranch_scc1 .LBB0_100
	s_load_dwordx2 s[8:9], s[2:3], 0x58
	v_readlane_b32 s6, v254, 9
	v_lshlrev_b32_e32 v4, 3, v0
	s_lshl_b32 s6, s6, 14
	v_and_b32_e32 v8, 31, v0
	v_lshrrev_b32_e32 v10, 3, v186
	v_and_b32_e32 v16, 56, v4
	s_add_i32 s6, s6, 0
	v_mov_b32_e32 v3, 0
	v_lshlrev_b32_e32 v2, 2, v8
	v_mul_u32_u24_e32 v4, 0x84, v16
	v_lshlrev_b32_e32 v5, 2, v10
	v_lshrrev_b32_e32 v1, 5, v186
	v_add_u32_e32 v9, s6, v2
	v_add3_u32 v11, s6, v4, v5
	s_waitcnt lgkmcnt(0)
	v_lshl_add_u64 v[4:5], s[8:9], 0, v[2:3]
	v_lshlrev_b32_e32 v2, 1, v16
	v_mul_u32_u24_e32 v15, 0x84, v1
	v_lshl_add_u64 v[6:7], s[4:5], 0, v[2:3]
	s_mov_b64 s[8:9], 0xd00000
	v_readlane_b32 s7, v254, 10
	v_lshl_add_u64 v[6:7], v[6:7], 0, s[8:9]
	v_readlane_b32 s8, v254, 11
	v_add_u32_e32 v15, v9, v15
	s_mov_b32 s7, 0
	v_or_b32_e32 v12, 8, v10
	v_or_b32_e32 v13, 16, v10
	v_or_b32_e32 v14, 24, v10
	s_lshl_b32 s10, s1, 1
	s_lshl_b32 s11, s1, 5
	s_add_i32 s12, s8, 0x18bf
	s_add_i32 s98, s1, 0x440
	s_cmp_ge_i32 s98, 0x540
	s_cselect_b32 s99, 0xfffffac0, 0
	s_add_i32 s98, s98, s99
	s_sub_i32 s99, s98, s1
	s_add_i32 s12, s12, s99
	s_lshl_b32 s10, s98, 1
	s_lshl_b32 s11, s98, 5
	s_movk_i32 s13, 0x7fff
	s_mov_b32 s14, 0xffff0000
	s_movk_i32 s15, 0x100
	s_mov_b32 s16, 0x200000
	v_lshlrev_b32_e32 v2, 2, v8
	s_movk_i32 s17, 0x2c00
	v_lshlrev_b32_e32 v8, 1, v16
	v_add_u32_e32 v16, 0x400, v15
	v_add_u32_e32 v17, 0x800, v15
	v_add_u32_e32 v18, 0xc00, v15
	v_add_u32_e32 v19, 0x1000, v15
	v_add_u32_e32 v20, 0x1400, v15
	v_add_u32_e32 v21, 0x1800, v15
	v_add_u32_e32 v22, 0x1c00, v15
	v_mov_b32_e32 v23, 0xaff
	v_readlane_b32 s9, v254, 12
	s_branch .LBB0_96

; #define LAS __attribute__((address_space(3)))
; #define P (*args_here())
; DI void p0_transposes(const Ptrs& P, LAS unsigned char* lds, int lo, int hi, int w, int NW, int wave, int lane) {
;     unsigned char* ws = P.ws;
;     LAS float* scr = (LAS float*)(lds + RING_OFF + wave * 16384);
;     for (int it = lo + w; it < hi; it += NW) {
;         int r = it;
;         if (r < 4 * P0_I_GU) {
;             const int which = r / P0_I_GU; r -= which * P0_I_GU; const int nblk = FF / 32, kb = r / nblk, nb = r % nblk;
;             const float* W = which == 0 ? P.in[9] : which == 1 ? P.in[10] : which == 2 ? P.in[32] : P.in[33];
;             bf16* WT = (bf16*)(ws + (which < 2 ? WS_WGUA : WS_WGUB));
;             p0_transpose_item(W, DM, FF, WT, kb, nb, gu_row(32 * nb, which & 1), scr, lane); continue; }
;         r -= 4 * P0_I_GU;
;         if (r < 2 * P0_I_D) { const int which = r / P0_I_D; r -= which * P0_I_D; const int nblk = DM / 32, kb = r / nblk, nb = r % nblk;
;             p0_transpose_item(which ? P.in[34] : P.in[11], FF, DM, (bf16*)(ws + (which ? WS_WDB : WS_WDA)), kb, nb, 32 * nb, scr, lane); continue; }
;         r -= 2 * P0_I_D;
;         { const int nblk = INC / 32, kb = r / nblk, nb = r % nblk; p0_transpose_item(P.in[12], DM, INC, (bf16*)(ws + WS_WIN), kb, nb, 32 * nb, scr, lane); }
;     }
; }
; DI void p0_tail1(const Ptrs& P, LAS unsigned char* lds, int bx, int tid, int wave, int lane) {
;     if (bx < 88) return;
;     const int w = (bx - 88) * NWAVES + wave, NW = 168 * NWAVES;
;     p0_transposes(P, lds, P0_DA, P0_DB, w, NW, wave, lane); p0_transposes(P, lds, P0_IN, P0_END, w, NW, wave, lane);
.LBB0_100:
	s_add_i32 s98, s1, 0x440
	s_cmp_ge_i32 s98, 0x540
	s_cselect_b32 s99, 0xfffffac0, 0
	s_add_i32 s98, s98, s99
	s_sub_i32 s99, s98, s1
	s_mov_b32 s1, s98
	s_addk_i32 s1, 0x2100
	s_cmpk_gt_i32 s1, 0x254f
	s_cbranch_scc1 .LBB0_111
	s_load_dwordx2 s[8:9], s[2:3], 0x60
	v_readlane_b32 s6, v254, 9
	s_lshl_b32 s1, s6, 14
	v_lshrrev_b32_e32 v1, 5, v186
	v_and_b32_e32 v2, 31, v0
	s_add_i32 s1, s1, 0
	v_mov_b32_e32 v5, 0
	v_lshlrev_b32_e32 v4, 2, v2
	v_mul_u32_u24_e32 v3, 0x84, v1
	s_waitcnt lgkmcnt(0)
	v_lshl_add_u64 v[6:7], s[8:9], 0, v[4:5]
	v_add3_u32 v3, s1, v4, v3
	v_lshlrev_b32_e32 v4, 3, v0
	v_and_b32_e32 v8, 56, v4
	v_lshlrev_b32_e32 v4, 1, v8
	v_lshrrev_b32_e32 v9, 3, v186
	v_lshl_add_u64 v[10:11], s[4:5], 0, v[4:5]
	s_mov_b64 s[8:9], 0x2400000
	v_readlane_b32 s7, v254, 10
	v_mul_u32_u24_e32 v12, 0x84, v8
	v_lshl_add_u64 v[10:11], v[10:11], 0, s[8:9]
	v_lshlrev_b32_e32 v4, 2, v9
	v_readlane_b32 s8, v254, 11
	s_mov_b32 s7, 0
	v_add3_u32 v12, s1, v12, v4
	v_or_b32_e32 v13, 8, v9
	v_or_b32_e32 v14, 16, v9
	v_or_b32_e32 v15, 24, v9
	s_add_i32 s1, s8, 0x23bf
	s_add_i32 s1, s1, s99
	s_movk_i32 s10, 0x4000
	s_mov_b32 s11, 0x8000
	s_mov_b32 s12, 0xc000
	s_mov_b32 s13, 0x11000
	s_mov_b32 s14, 0x15000
	s_mov_b32 s15, 0x19000
	s_mov_b32 s16, 0x1e000
	s_mov_b32 s17, 0x22000
	s_mov_b32 s18, 0x26000
	s_mov_b32 s19, 0x2b000
	s_mov_b32 s20, 0x2f000
	s_mov_b32 s21, 0x33000
	s_mov_b32 s22, 0x38000
	s_mov_b32 s23, 0x3c000
	s_mov_b32 s24, 0x40000
	s_mov_b32 s25, 0x45000
	s_mov_b32 s26, 0x49000
	s_mov_b32 s27, 0x4d000
	s_mov_b32 s28, 0x51000
	s_mov_b32 s29, 0x56000
	s_mov_b32 s30, 0x5a000
	s_mov_b32 s31, 0x5e000
	s_mov_b32 s34, 0x63000
	s_mov_b32 s35, 0x67000
	s_mov_b32 s36, 0x6b000
	s_mov_b32 s37, 0x70000
	s_mov_b32 s38, 0x74000
	s_mov_b32 s39, 0x78000
	s_mov_b32 s40, 0x7d000
	s_mov_b32 s41, 0x81000
	s_mov_b32 s42, 0x85000
	s_movk_i32 s43, 0x7fff
	s_mov_b32 s48, 0xffff0000
	s_mov_b32 s49, 0xd00000
	s_movk_i32 s50, 0x58
	s_movk_i32 s51, 0x100
	s_mov_b32 s52, 0x200000
	s_movk_i32 s53, 0x2c00
	v_add_u32_e32 v16, 0x400, v3
	v_add_u32_e32 v17, 0x800, v3
	v_add_u32_e32 v18, 0xc00, v3
	v_add_u32_e32 v19, 0x1000, v3
	v_add_u32_e32 v20, 0x1400, v3
	v_add_u32_e32 v21, 0x1800, v3
	v_add_u32_e32 v22, 0x1c00, v3
	v_mov_b32_e32 v23, 0xaff
	v_readlane_b32 s9, v254, 12
	s_branch .LBB0_103
